# v18: GEMM LDS-DMA counted waits restored + convert_uv u-row loads and lru input loads de-serialized
# speedup vs baseline: 1.0318x; 1.0318x over previous
; __device__ __forceinline__ float bf2f(bf16_t v) { return __uint_as_float(((unsigned)v) << 16); }
; __device__ void lru_local_unit(const Params& p, unsigned char* smem, int unit) {
;     ...
;   for (int e = tid; e < 131 * 64; e += HTHR) {
;     const int r = e >> 6, j = e & 63, tt = r - 3;
;     float v = 0.f;
;     if (c * 128 + tt >= 0) v = bf2f(proj[(size_t)(t0 + tt) * LDP + ch0 + j]);
;     R1[e] = v;
;   }
.LBB0_499:
	v_add_u32_e32 v2, s84, v165
	v_and_b32_e32 v16, 15, v2
	v_lshlrev_b32_e32 v127, 3, v2
	s_movk_i32 s3, 0xf87f
	v_lshlrev_b32_e32 v68, 7, v16
	v_and_b32_e32 v29, 0xffffff80, v116
	v_bitop3_b32 v4, v127, s3, v127 bitop3:0xcf
	v_lshl_add_u64 v[2:3], v[70:71], 0, v[68:69]
	v_mov_b32_e32 v27, v104
	v_mov_b32_e32 v26, v112
	v_mov_b32_e32 v5, v117
	s_waitcnt lgkmcnt(0)
	s_and_saveexec_b64 s[66:67], s[4:5]
	s_cbranch_execz .LBB0_505
	v_mov_b32_e32 v5, v114
	v_mov_b32_e32 v6, v117
	v_mov_b32_e32 v7, v115
	v_mov_b32_e32 v27, v104
	v_add_u32_e32 v32, 0, v6
	v_cmp_lt_u32_e32 vcc, 0, v5
	v_cmp_gt_i32_e64 s[80:81], v32, v4
	v_mov_b32_e32 v140, 0
	s_nop 1
	s_and_b64 vcc, vcc, s[80:81]
	s_and_saveexec_b64 s[80:81], vcc
	v_add_u32_e32 v32, v29, v32
	v_mad_i64_i32 v[32:33], s[12:13], v32, s89, v[2:3]
	global_load_ushort v140, v[32:33], off
	s_or_b64 exec, exec, s[80:81]
	v_add_u32_e32 v32, 4, v6
	v_cmp_lt_u32_e32 vcc, 1, v5
	v_cmp_gt_i32_e64 s[80:81], v32, v4
	v_mov_b32_e32 v141, 0
	s_nop 1
	s_and_b64 vcc, vcc, s[80:81]
	s_and_saveexec_b64 s[80:81], vcc
	v_add_u32_e32 v32, v29, v32
	v_mad_i64_i32 v[32:33], s[12:13], v32, s89, v[2:3]
	global_load_ushort v141, v[32:33], off
	s_or_b64 exec, exec, s[80:81]
	v_add_u32_e32 v32, 8, v6
	v_cmp_lt_u32_e32 vcc, 2, v5
	v_cmp_gt_i32_e64 s[80:81], v32, v4
	v_mov_b32_e32 v142, 0
	s_nop 1
	s_and_b64 vcc, vcc, s[80:81]
	s_and_saveexec_b64 s[80:81], vcc
	v_add_u32_e32 v32, v29, v32
	v_mad_i64_i32 v[32:33], s[12:13], v32, s89, v[2:3]
	global_load_ushort v142, v[32:33], off
	s_or_b64 exec, exec, s[80:81]
	v_add_u32_e32 v32, 12, v6
	v_cmp_lt_u32_e32 vcc, 3, v5
	v_cmp_gt_i32_e64 s[80:81], v32, v4
	v_mov_b32_e32 v143, 0
	s_nop 1
	s_and_b64 vcc, vcc, s[80:81]
	s_and_saveexec_b64 s[80:81], vcc
	v_add_u32_e32 v32, v29, v32
	v_mad_i64_i32 v[32:33], s[12:13], v32, s89, v[2:3]
	global_load_ushort v143, v[32:33], off
	s_or_b64 exec, exec, s[80:81]
	v_add_u32_e32 v32, 16, v6
	v_cmp_lt_u32_e32 vcc, 4, v5
	v_cmp_gt_i32_e64 s[80:81], v32, v4
	v_mov_b32_e32 v144, 0
	s_nop 1
	s_and_b64 vcc, vcc, s[80:81]
	s_and_saveexec_b64 s[80:81], vcc
	v_add_u32_e32 v32, v29, v32
	v_mad_i64_i32 v[32:33], s[12:13], v32, s89, v[2:3]
	global_load_ushort v144, v[32:33], off
	s_or_b64 exec, exec, s[80:81]
	v_add_u32_e32 v32, 20, v6
	v_cmp_lt_u32_e32 vcc, 5, v5
	v_cmp_gt_i32_e64 s[80:81], v32, v4
	v_mov_b32_e32 v145, 0
	s_nop 1
	s_and_b64 vcc, vcc, s[80:81]
	s_and_saveexec_b64 s[80:81], vcc
	v_add_u32_e32 v32, v29, v32
	v_mad_i64_i32 v[32:33], s[12:13], v32, s89, v[2:3]
	global_load_ushort v145, v[32:33], off
	s_or_b64 exec, exec, s[80:81]
	v_add_u32_e32 v32, 24, v6
	v_cmp_lt_u32_e32 vcc, 6, v5
	v_cmp_gt_i32_e64 s[80:81], v32, v4
	v_mov_b32_e32 v146, 0
	s_nop 1
	s_and_b64 vcc, vcc, s[80:81]
	s_and_saveexec_b64 s[80:81], vcc
	v_add_u32_e32 v32, v29, v32
	v_mad_i64_i32 v[32:33], s[12:13], v32, s89, v[2:3]
	global_load_ushort v146, v[32:33], off
	s_or_b64 exec, exec, s[80:81]
	v_add_u32_e32 v32, 28, v6
	v_cmp_lt_u32_e32 vcc, 7, v5
	v_cmp_gt_i32_e64 s[80:81], v32, v4
	v_mov_b32_e32 v147, 0
	s_nop 1
	s_and_b64 vcc, vcc, s[80:81]
	s_and_saveexec_b64 s[80:81], vcc
	v_add_u32_e32 v32, v29, v32
	v_mad_i64_i32 v[32:33], s[12:13], v32, s89, v[2:3]
	global_load_ushort v147, v[32:33], off
	s_or_b64 exec, exec, s[80:81]
	v_add_u32_e32 v32, 32, v6
	v_cmp_lt_u32_e32 vcc, 8, v5
	v_cmp_gt_i32_e64 s[80:81], v32, v4
	v_mov_b32_e32 v148, 0
	s_nop 1
	s_and_b64 vcc, vcc, s[80:81]
	s_and_saveexec_b64 s[80:81], vcc
	v_add_u32_e32 v32, v29, v32
	v_mad_i64_i32 v[32:33], s[12:13], v32, s89, v[2:3]
	global_load_ushort v148, v[32:33], off
	s_or_b64 exec, exec, s[80:81]
	v_add_u32_e32 v32, 36, v6
	v_cmp_lt_u32_e32 vcc, 9, v5
	v_cmp_gt_i32_e64 s[80:81], v32, v4
	v_mov_b32_e32 v149, 0
	s_nop 1
	s_and_b64 vcc, vcc, s[80:81]
	s_and_saveexec_b64 s[80:81], vcc
	v_add_u32_e32 v32, v29, v32
	v_mad_i64_i32 v[32:33], s[12:13], v32, s89, v[2:3]
	global_load_ushort v149, v[32:33], off
	s_or_b64 exec, exec, s[80:81]
	s_waitcnt vmcnt(0)
	v_cmp_lt_u32_e32 vcc, 0, v5
	v_lshlrev_b32_e32 v140, 16, v140
	s_and_saveexec_b64 s[80:81], vcc
	ds_write_b32 v7, v140
	s_or_b64 exec, exec, s[80:81]
	v_cmp_lt_u32_e32 vcc, 1, v5
	v_lshlrev_b32_e32 v141, 16, v141
	s_and_saveexec_b64 s[80:81], vcc
	ds_write_b32 v7, v141 offset:1024
	s_or_b64 exec, exec, s[80:81]
	v_cmp_lt_u32_e32 vcc, 2, v5
	v_lshlrev_b32_e32 v142, 16, v142
	s_and_saveexec_b64 s[80:81], vcc
	ds_write_b32 v7, v142 offset:2048
	s_or_b64 exec, exec, s[80:81]
	v_cmp_lt_u32_e32 vcc, 3, v5
	v_lshlrev_b32_e32 v143, 16, v143
	s_and_saveexec_b64 s[80:81], vcc
	ds_write_b32 v7, v143 offset:3072
	s_or_b64 exec, exec, s[80:81]
	v_cmp_lt_u32_e32 vcc, 4, v5
	v_lshlrev_b32_e32 v144, 16, v144
	s_and_saveexec_b64 s[80:81], vcc
	ds_write_b32 v7, v144 offset:4096
	s_or_b64 exec, exec, s[80:81]
	v_cmp_lt_u32_e32 vcc, 5, v5
	v_lshlrev_b32_e32 v145, 16, v145
	s_and_saveexec_b64 s[80:81], vcc
	ds_write_b32 v7, v145 offset:5120
	s_or_b64 exec, exec, s[80:81]
	v_cmp_lt_u32_e32 vcc, 6, v5
	v_lshlrev_b32_e32 v146, 16, v146
	s_and_saveexec_b64 s[80:81], vcc
	ds_write_b32 v7, v146 offset:6144
	s_or_b64 exec, exec, s[80:81]
	v_cmp_lt_u32_e32 vcc, 7, v5
	v_lshlrev_b32_e32 v147, 16, v147
	s_and_saveexec_b64 s[80:81], vcc
	ds_write_b32 v7, v147 offset:7168
	s_or_b64 exec, exec, s[80:81]
	v_cmp_lt_u32_e32 vcc, 8, v5
	v_lshlrev_b32_e32 v148, 16, v148
	s_and_saveexec_b64 s[80:81], vcc
	ds_write_b32 v7, v148 offset:8192
	s_or_b64 exec, exec, s[80:81]
	v_cmp_lt_u32_e32 vcc, 9, v5
	v_lshlrev_b32_e32 v149, 16, v149
	s_and_saveexec_b64 s[80:81], vcc
	ds_write_b32 v7, v149 offset:9216
	s_or_b64 exec, exec, s[80:81]
	v_lshl_add_u32 v27, v5, 8, v27
	v_lshrrev_b32_e32 v5, 6, v27
	v_lshlrev_b32_e32 v26, 2, v27
	v_add_u32_e32 v5, -3, v5

; __device__ __forceinline__ float bf2f(bf16_t v) { return __uint_as_float(((unsigned)v) << 16); }
; __device__ void lru_local_unit(const Params& p, unsigned char* smem, int unit) {
;     ...
;   for (int e = tid; e < 131 * 64; e += HTHR) {
;     const int r = e >> 6, j = e & 63, tt = r - 3;
;     float v = 0.f;
;     if (c * 128 + tt >= 0) v = bf2f(proj[(size_t)(t0 + tt) * LDP + ch0 + j]);
;     R1[e] = v;
;   }
.LBB0_507:
	v_add_u32_e32 v32, s3, v5
	v_cmp_gt_i32_e32 vcc, v32, v4
	v_mov_b32_e32 v140, 0
	s_and_saveexec_b64 s[78:79], vcc
	v_add_u32_e32 v32, s3, v29
	v_mad_i64_i32 v[32:33], s[12:13], v32, s89, v[2:3]
	global_load_ushort v140, v[32:33], off
	s_or_b64 exec, exec, s[78:79]
	v_add_u32_e32 v32, s3, v27
	v_cmp_gt_i32_e32 vcc, v32, v4
	v_mov_b32_e32 v141, 0
	s_and_saveexec_b64 s[78:79], vcc
	v_add_u32_e32 v32, s3, v28
	v_mad_i64_i32 v[32:33], s[12:13], v32, s89, v[2:3]
	global_load_ushort v141, v[32:33], off
	s_or_b64 exec, exec, s[78:79]
	v_add_u32_e32 v32, s3, v24
	v_cmp_gt_i32_e32 vcc, v32, v4
	v_mov_b32_e32 v142, 0
	s_and_saveexec_b64 s[78:79], vcc
	v_add_u32_e32 v32, s3, v25
	v_mad_i64_i32 v[32:33], s[12:13], v32, s89, v[2:3]
	global_load_ushort v142, v[32:33], off
	s_or_b64 exec, exec, s[78:79]
	v_add_u32_e32 v32, s3, v22
	v_cmp_gt_i32_e32 vcc, v32, v4
	v_mov_b32_e32 v143, 0
	s_and_saveexec_b64 s[78:79], vcc
	v_add_u32_e32 v32, s3, v23
	v_mad_i64_i32 v[32:33], s[12:13], v32, s89, v[2:3]
	global_load_ushort v143, v[32:33], off
	s_or_b64 exec, exec, s[78:79]
	v_add_u32_e32 v32, s3, v20
	v_cmp_gt_i32_e32 vcc, v32, v4
	v_mov_b32_e32 v144, 0
	s_and_saveexec_b64 s[78:79], vcc
	v_add_u32_e32 v32, s3, v21
	v_mad_i64_i32 v[32:33], s[12:13], v32, s89, v[2:3]
	global_load_ushort v144, v[32:33], off
	s_or_b64 exec, exec, s[78:79]
	v_add_u32_e32 v32, s3, v18
	v_cmp_gt_i32_e32 vcc, v32, v4
	v_mov_b32_e32 v145, 0
	s_and_saveexec_b64 s[78:79], vcc
	v_add_u32_e32 v32, s3, v19
	v_mad_i64_i32 v[32:33], s[12:13], v32, s89, v[2:3]
	global_load_ushort v145, v[32:33], off
	s_or_b64 exec, exec, s[78:79]
	v_add_u32_e32 v32, s3, v15
	v_cmp_gt_i32_e32 vcc, v32, v4
	v_mov_b32_e32 v146, 0
	s_and_saveexec_b64 s[78:79], vcc
	v_add_u32_e32 v32, s3, v17
	v_mad_i64_i32 v[32:33], s[12:13], v32, s89, v[2:3]
	global_load_ushort v146, v[32:33], off
	s_or_b64 exec, exec, s[78:79]
	v_add_u32_e32 v32, s3, v13
	v_cmp_gt_i32_e32 vcc, v32, v4
	v_mov_b32_e32 v147, 0
	s_and_saveexec_b64 s[78:79], vcc
	v_add_u32_e32 v32, s3, v14
	v_mad_i64_i32 v[32:33], s[12:13], v32, s89, v[2:3]
	global_load_ushort v147, v[32:33], off
	s_or_b64 exec, exec, s[78:79]
	v_add_u32_e32 v32, s3, v11
	v_cmp_gt_i32_e32 vcc, v32, v4
	v_mov_b32_e32 v148, 0
	s_and_saveexec_b64 s[78:79], vcc
	v_add_u32_e32 v32, s3, v12
	v_mad_i64_i32 v[32:33], s[12:13], v32, s89, v[2:3]
	global_load_ushort v148, v[32:33], off
	s_or_b64 exec, exec, s[78:79]
	v_add_u32_e32 v32, s3, v9
	v_cmp_gt_i32_e32 vcc, v32, v4
	v_mov_b32_e32 v149, 0
	s_and_saveexec_b64 s[78:79], vcc
	v_add_u32_e32 v32, s3, v10
	v_mad_i64_i32 v[32:33], s[12:13], v32, s89, v[2:3]
	global_load_ushort v149, v[32:33], off
	s_or_b64 exec, exec, s[78:79]
	v_add_u32_e32 v32, s3, v7
	v_cmp_gt_i32_e32 vcc, v32, v4
	v_mov_b32_e32 v150, 0
	s_and_saveexec_b64 s[78:79], vcc
	v_add_u32_e32 v32, s3, v8
	v_mad_i64_i32 v[32:33], s[12:13], v32, s89, v[2:3]
	global_load_ushort v150, v[32:33], off
	s_or_b64 exec, exec, s[78:79]
	s_waitcnt vmcnt(0)
	v_lshlrev_b32_e32 v140, 16, v140
	ds_write_b32 v26, v140
	v_lshlrev_b32_e32 v141, 16, v141
	ds_write_b32 v26, v141 offset:1024
	v_lshlrev_b32_e32 v142, 16, v142
	ds_write_b32 v26, v142 offset:2048
	v_lshlrev_b32_e32 v143, 16, v143
	ds_write_b32 v26, v143 offset:3072
	v_lshlrev_b32_e32 v144, 16, v144
	ds_write_b32 v26, v144 offset:4096
	v_lshlrev_b32_e32 v145, 16, v145
	ds_write_b32 v26, v145 offset:5120
	v_lshlrev_b32_e32 v146, 16, v146
	ds_write_b32 v26, v146 offset:6144
	v_lshlrev_b32_e32 v147, 16, v147
	ds_write_b32 v26, v147 offset:7168
	v_lshlrev_b32_e32 v148, 16, v148
	ds_write_b32 v26, v148 offset:8192
	v_lshlrev_b32_e32 v149, 16, v149
	ds_write_b32 v26, v149 offset:9216
	v_lshlrev_b32_e32 v30, 16, v150
	s_branch .LBB0_506

; __device__ void convert_uv(const Params& p, int part, int nparts) {
;     ...
;   for (int row = blockIdx.x * 8 + wid + part * (int)gridDim.x * 8; row < 32768; row += nparts * (int)gridDim.x * 8) {
;     const bool isv = row >= 16384;
;     const int e = row & 16383;
;     const float* src = (isv ? p.peer_v : p.peer_u) + (size_t)e * DM + lane * 32;
;     float vals[32];
;     float ss = 0.f;
; #pragma unroll
;     for (int q = 0; q < 8; ++q) {
;       f32x4 t = *(const f32x4*)(src + q * 4);
;       if (!isv) t *= *(const f32x4*)(p.norm_ffn_w + lane * 32 + q * 4);
.LBB0_1109:
	s_mul_i32 s0, s48, s96
	s_add_i32 s0, s0, s2
	v_lshl_add_u32 v38, s0, 3, v164
	v_cmp_gt_i32_e32 vcc, s59, v38
	s_and_saveexec_b64 s[10:11], vcc
	s_cbranch_execz .LBB0_1084
	v_ashrrev_i32_e32 v79, 31, v78
	v_lshlrev_b64 v[2:3], 10, v[78:79]
	v_lshl_add_u64 v[34:35], v[78:79], 2, s[18:19]
	v_lshl_add_u64 v[36:37], v[82:83], 0, v[2:3]
	s_mov_b64 s[46:47], 0
	v_mov_b32_e32 v39, v75
	global_load_dwordx4 v[168:171], v[76:77], off
	global_load_dwordx4 v[172:175], v[76:77], off offset:16
	global_load_dwordx4 v[176:179], v[76:77], off offset:32
	global_load_dwordx4 v[180:183], v[76:77], off offset:48
	global_load_dwordx4 v[184:187], v[76:77], off offset:64
	global_load_dwordx4 v[188:191], v[76:77], off offset:80
	global_load_dwordx4 v[192:195], v[76:77], off offset:96
	global_load_dwordx4 v[196:199], v[76:77], off offset:112
	s_branch .LBB0_1112

; __device__ void convert_uv(const Params& p, int part, int nparts) {
;     ...
;   for (int row = blockIdx.x * 8 + wid + part * (int)gridDim.x * 8; row < 32768; row += nparts * (int)gridDim.x * 8) {
;     const bool isv = row >= 16384;
;     const int e = row & 16383;
;     const float* src = (isv ? p.peer_v : p.peer_u) + (size_t)e * DM + lane * 32;
;     float vals[32];
;     float ss = 0.f;
; #pragma unroll
;     for (int q = 0; q < 8; ++q) {
;       f32x4 t = *(const f32x4*)(src + q * 4);
;       if (!isv) t *= *(const f32x4*)(p.norm_ffn_w + lane * 32 + q * 4);
; #pragma unroll
;       for (int k = 0; k < 4; ++k) {
;         vals[q * 4 + k] = t[k];
;         ss += t[k] * t[k];
;       }
;     }
;     ss = wave_sum(ss);
;     const float rms = sqrtf(ss * (1.f / 2048.f));
;     const float sc = rms * (2.6f / 7.f);
;     const float inv = sc > 0.f ? 1.f / sc : 0.f;
.LBB0_1112:
	v_mov_b32_e32 v2, s25
	v_mov_b32_e32 v3, s27
	v_cmp_lt_i32_e64 s[8:9], s62, v38
	s_waitcnt lgkmcnt(0)
	v_mov_b32_e32 v4, s26
	v_mov_b32_e32 v89, v63
	v_cndmask_b32_e64 v3, v2, v3, s[8:9]
	v_mov_b32_e32 v2, s24
	v_cndmask_b32_e64 v2, v2, v4, s[8:9]
	v_and_b32_e32 v4, 0x1fff800, v39
	v_lshlrev_b32_e32 v62, 2, v4
	v_lshl_add_u64 v[2:3], v[2:3], 0, v[62:63]
	v_lshl_add_u64 v[6:7], v[2:3], 0, v[88:89]
	global_load_dwordx4 v[26:29], v[6:7], off
	v_cmp_gt_i32_e32 vcc, s53, v38
	global_load_dwordx4 v[30:33], v[6:7], off offset:16
	global_load_dwordx4 v[18:21], v[6:7], off offset:32
	global_load_dwordx4 v[22:25], v[6:7], off offset:48
	global_load_dwordx4 v[10:13], v[6:7], off offset:64
	global_load_dwordx4 v[14:17], v[6:7], off offset:80
	global_load_dwordx4 v[2:5], v[6:7], off offset:96
	global_load_dwordx4 v[6:9], v[6:7], off offset:112
	s_and_saveexec_b64 s[0:1], vcc
	s_cbranch_execz .LBB0_1121
	s_waitcnt vmcnt(0)
	v_pk_mul_f32 v[26:27], v[26:27], v[168:169]
	v_pk_mul_f32 v[28:29], v[28:29], v[170:171]
	v_pk_mul_f32 v[30:31], v[30:31], v[172:173]
	v_pk_mul_f32 v[32:33], v[32:33], v[174:175]
	v_pk_mul_f32 v[18:19], v[18:19], v[176:177]
	v_pk_mul_f32 v[20:21], v[20:21], v[178:179]
	v_pk_mul_f32 v[22:23], v[22:23], v[180:181]
	v_pk_mul_f32 v[24:25], v[24:25], v[182:183]
	v_pk_mul_f32 v[10:11], v[10:11], v[184:185]
	v_pk_mul_f32 v[12:13], v[12:13], v[186:187]
	v_pk_mul_f32 v[14:15], v[14:15], v[188:189]
	v_pk_mul_f32 v[16:17], v[16:17], v[190:191]
	v_pk_mul_f32 v[2:3], v[2:3], v[192:193]
	v_pk_mul_f32 v[4:5], v[4:5], v[194:195]
	v_pk_mul_f32 v[6:7], v[6:7], v[196:197]
	v_pk_mul_f32 v[8:9], v[8:9], v[198:199]
.LBB0_1121:
	s_or_b64 exec, exec, s[0:1]
	s_waitcnt vmcnt(7)
	v_mul_f32_e32 v44, v27, v27
	v_fmac_f32_e32 v44, v26, v26
	v_fmac_f32_e32 v44, v28, v28
	v_fmac_f32_e32 v44, v29, v29
	s_waitcnt vmcnt(6)
	v_fmac_f32_e32 v44, v30, v30
	v_fmac_f32_e32 v44, v31, v31
	v_fmac_f32_e32 v44, v32, v32
	v_fmac_f32_e32 v44, v33, v33
	s_waitcnt vmcnt(5)
	v_fmac_f32_e32 v44, v18, v18
	v_fmac_f32_e32 v44, v19, v19
	v_fmac_f32_e32 v44, v20, v20
	v_fmac_f32_e32 v44, v21, v21
	s_waitcnt vmcnt(4)
	v_fmac_f32_e32 v44, v22, v22
	v_fmac_f32_e32 v44, v23, v23
	v_fmac_f32_e32 v44, v24, v24
	v_fmac_f32_e32 v44, v25, v25
	s_waitcnt vmcnt(3)
	v_fmac_f32_e32 v44, v10, v10
	v_fmac_f32_e32 v44, v11, v11
	v_fmac_f32_e32 v44, v12, v12
	v_fmac_f32_e32 v44, v13, v13
	s_waitcnt vmcnt(2)
	v_fmac_f32_e32 v44, v14, v14
	v_fmac_f32_e32 v44, v15, v15
	v_fmac_f32_e32 v44, v16, v16
	v_fmac_f32_e32 v44, v17, v17
	s_waitcnt vmcnt(1)
	v_fmac_f32_e32 v44, v2, v2
	v_fmac_f32_e32 v44, v3, v3
	v_fmac_f32_e32 v44, v4, v4
	v_fmac_f32_e32 v44, v5, v5
	s_waitcnt vmcnt(0)
	v_pk_mul_f32 v[42:43], v[6:7], v[6:7]
	v_pk_mul_f32 v[40:41], v[8:9], v[8:9]
	v_add_f32_e32 v42, v44, v42
	v_add_f32_e32 v42, v43, v42
	v_add_f32_e32 v40, v40, v42
	v_add_f32_e32 v40, v41, v40
	ds_bpermute_b32 v41, v106, v40
	s_waitcnt lgkmcnt(0)
	v_add_f32_e32 v40, v40, v41
	ds_bpermute_b32 v41, v107, v40
	s_waitcnt lgkmcnt(0)
	v_add_f32_e32 v40, v40, v41
	ds_bpermute_b32 v41, v108, v40
	s_waitcnt lgkmcnt(0)
	v_add_f32_e32 v40, v40, v41
	ds_bpermute_b32 v41, v109, v40
	s_waitcnt lgkmcnt(0)
	v_add_f32_e32 v40, v40, v41
	ds_bpermute_b32 v41, v110, v40
	s_waitcnt lgkmcnt(0)
	v_add_f32_e32 v40, v40, v41
	ds_bpermute_b32 v41, v111, v40
	s_waitcnt lgkmcnt(0)
	v_add_f32_e32 v40, v40, v41
	v_mul_f32_e32 v40, 0x3a000000, v40
	v_mul_f32_e32 v41, 0x4f800000, v40
	v_cmp_gt_f32_e32 vcc, s63, v40
	s_nop 1
	v_cndmask_b32_e32 v40, v40, v41, vcc
	v_sqrt_f32_e32 v41, v40
	s_nop 0
	v_add_u32_e32 v42, -1, v41
	v_add_u32_e32 v43, 1, v41
	v_fma_f32 v44, -v42, v41, v40
	v_fma_f32 v45, -v43, v41, v40
	v_cmp_ge_f32_e64 s[0:1], 0, v44
	s_nop 1
	v_cndmask_b32_e64 v41, v41, v42, s[0:1]
	v_cmp_lt_f32_e64 s[0:1], 0, v45
	s_nop 1
	v_cndmask_b32_e64 v41, v41, v43, s[0:1]
	v_mul_f32_e32 v42, 0x37800000, v41
	v_cndmask_b32_e32 v41, v41, v42, vcc
	v_cmp_class_f32_e32 vcc, v40, v119
	s_nop 1
	v_cndmask_b32_e32 v40, v41, v40, vcc
	v_mul_f32_e32 v40, 0x3ebe2be2, v40
	v_div_scale_f32 v41, s[0:1], v40, v40, 1.0
	v_rcp_f32_e32 v42, v41
	v_div_scale_f32 v43, vcc, 1.0, v40, 1.0
	v_fma_f32 v44, -v41, v42, 1.0
	v_fmac_f32_e32 v42, v44, v42
	v_mul_f32_e32 v44, v43, v42
	v_fma_f32 v45, -v41, v44, v43
	v_fmac_f32_e32 v44, v45, v42
	v_fma_f32 v41, -v41, v44, v43
	v_div_fmas_f32 v41, v41, v42, v44
	v_div_fixup_f32 v41, v41, v40, 1.0
	v_cmp_lt_f32_e32 vcc, 0, v40
	s_nop 1
	v_cndmask_b32_e32 v41, 0, v41, vcc
	v_mul_f32_e32 v26, v26, v41
	v_rndne_f32_e32 v26, v26
	v_mul_f32_e32 v28, v28, v41
	v_med3_f32 v26, v26, s64, v120
	v_rndne_f32_e32 v28, v28
	v_mul_f32_e32 v32, v32, v41
	v_mul_f32_e32 v27, v27, v41
	v_mul_f32_e32 v31, v31, v41
	v_cvt_i32_f32_e32 v26, v26
	v_med3_f32 v28, v28, s64, v120
	v_rndne_f32_e32 v32, v32
	v_rndne_f32_e32 v27, v27
	v_rndne_f32_e32 v31, v31
	v_cvt_i32_f32_e32 v28, v28
	v_med3_f32 v32, v32, s64, v120
	v_med3_f32 v27, v27, s64, v120
	v_med3_f32 v31, v31, s64, v120
	v_cvt_i32_f32_e32 v32, v32
	v_cvt_i32_f32_e32 v27, v27
	v_cvt_i32_f32_e32 v31, v31
	v_mul_f32_e32 v18, v18, v41
	v_add_u32_e32 v42, 8, v26
	v_and_b32_e32 v26, 15, v26
	v_rndne_f32_e32 v18, v18
	v_mul_f32_e32 v22, v22, v41
	v_cndmask_b32_e64 v26, v26, v42, s[8:9]
	v_add_u32_e32 v42, 8, v28
	v_and_b32_e32 v28, 15, v28
	v_med3_f32 v18, v18, s64, v120
	v_rndne_f32_e32 v22, v22
	v_mul_f32_e32 v19, v19, v41
	v_cndmask_b32_e64 v28, v28, v42, s[8:9]
	v_add_u32_e32 v42, 8, v32
	v_and_b32_e32 v32, 15, v32
	v_cvt_i32_f32_e32 v18, v18
	v_med3_f32 v22, v22, s64, v120
	v_rndne_f32_e32 v19, v19
	v_mul_f32_e32 v23, v23, v41
	v_add_u32_e32 v44, 8, v27
	v_and_b32_e32 v27, 15, v27
	v_add_u32_e32 v45, 8, v31
; __device__ void convert_uv(const Params& p, int part, int nparts) {
;     ...
;     u32x4 o;
; #pragma unroll
;     for (int m = 0; m < 4; ++m) {
;       unsigned w = 0;
; #pragma unroll
;       for (int j = 0; j < 4; ++j) {
;         const float lo = fminf(fmaxf(rintf(vals[m * 8 + j] * inv), -7.f), 7.f);
;         const float hi = fminf(fmaxf(rintf(vals[m * 8 + 4 + j] * inv), -7.f), 7.f);
;         const unsigned bl = isv ? (unsigned)((int)lo + 8) : ((unsigned)(int)lo & 0xfu);
;         const unsigned bh = isv ? (unsigned)((int)hi + 8) : ((unsigned)(int)hi & 0xfu);
;         w |= (bl | (bh << 4)) << (8 * j);
;       }
;       o[m] = w;
;     }
;     *(u32x4*)(tb + (size_t)row * 1024 + lane * 16) = o;
;     if (lane == 0) scales[row] = sc;
	v_and_b32_e32 v31, 15, v31
	v_cndmask_b32_e64 v32, v32, v42, s[8:9]
	v_cvt_i32_f32_e32 v22, v22
	v_med3_f32 v19, v19, s64, v120
	v_rndne_f32_e32 v23, v23
	v_mul_f32_e32 v20, v20, v41
	v_cndmask_b32_e64 v27, v27, v44, s[8:9]
	v_cndmask_b32_e64 v31, v31, v45, s[8:9]
	v_lshlrev_b32_e32 v32, 20, v32
	v_lshlrev_b32_e32 v28, 16, v28
	v_cvt_i32_f32_e32 v19, v19
	v_med3_f32 v23, v23, s64, v120
	v_rndne_f32_e32 v20, v20
	v_mul_f32_e32 v24, v24, v41
	v_lshlrev_b32_e32 v31, 12, v31
	v_lshlrev_b32_e32 v27, 8, v27
	v_or3_b32 v26, v28, v26, v32
	v_cvt_i32_f32_e32 v23, v23
	v_med3_f32 v20, v20, s64, v120
	v_rndne_f32_e32 v24, v24
	v_mul_f32_e32 v21, v21, v41
	v_mul_f32_e32 v25, v25, v41
	v_or3_b32 v26, v26, v27, v31
	v_add_u32_e32 v27, 8, v18
	v_and_b32_e32 v18, 15, v18
	v_cvt_i32_f32_e32 v20, v20
	v_med3_f32 v24, v24, s64, v120
	v_rndne_f32_e32 v21, v21
	v_rndne_f32_e32 v25, v25
	v_cndmask_b32_e64 v18, v18, v27, s[8:9]
	v_add_u32_e32 v27, 8, v22
	v_and_b32_e32 v22, 15, v22
	v_cvt_i32_f32_e32 v24, v24
	v_med3_f32 v21, v21, s64, v120
	v_med3_f32 v25, v25, s64, v120
	v_cndmask_b32_e64 v22, v22, v27, s[8:9]
	v_add_u32_e32 v27, 8, v19
	v_and_b32_e32 v19, 15, v19
	v_cvt_i32_f32_e32 v21, v21
	v_cvt_i32_f32_e32 v25, v25
	v_cndmask_b32_e64 v19, v19, v27, s[8:9]
	v_add_u32_e32 v27, 8, v23
	v_and_b32_e32 v23, 15, v23
	v_mul_f32_e32 v10, v10, v41
	v_cndmask_b32_e64 v23, v23, v27, s[8:9]
	v_add_u32_e32 v27, 8, v20
	v_and_b32_e32 v20, 15, v20
	v_rndne_f32_e32 v10, v10
	v_mul_f32_e32 v14, v14, v41
	v_cndmask_b32_e64 v20, v20, v27, s[8:9]
	v_add_u32_e32 v27, 8, v24
	v_and_b32_e32 v24, 15, v24
	v_med3_f32 v10, v10, s64, v120
	v_rndne_f32_e32 v14, v14
	v_mul_f32_e32 v11, v11, v41
	v_cndmask_b32_e64 v24, v24, v27, s[8:9]
	v_add_u32_e32 v27, 8, v21
	v_lshlrev_b32_e32 v25, 4, v25
	v_cvt_i32_f32_e32 v10, v10
	v_med3_f32 v14, v14, s64, v120
	v_rndne_f32_e32 v11, v11
	v_mul_f32_e32 v15, v15, v41
	v_lshlrev_b32_e32 v24, 20, v24
	v_lshlrev_b32_e32 v20, 16, v20
	v_bitop3_b32 v27, v25, v27, s65 bitop3:0xde
	v_and_or_b32 v21, v21, 15, v25
	v_cvt_i32_f32_e32 v14, v14
	v_med3_f32 v11, v11, s64, v120
	v_rndne_f32_e32 v15, v15
	v_mul_f32_e32 v12, v12, v41
	v_lshlrev_b32_e32 v23, 12, v23
	v_lshlrev_b32_e32 v19, 8, v19
	v_cndmask_b32_e64 v21, v21, v27, s[8:9]
	v_or3_b32 v18, v20, v18, v24
	v_cvt_i32_f32_e32 v11, v11
	v_med3_f32 v15, v15, s64, v120
	v_rndne_f32_e32 v12, v12
	v_mul_f32_e32 v16, v16, v41
	v_lshlrev_b32_e32 v22, 4, v22
	v_lshlrev_b32_e32 v21, 24, v21
	v_or3_b32 v18, v18, v19, v23
	v_cvt_i32_f32_e32 v15, v15
	v_med3_f32 v12, v12, s64, v120
	v_rndne_f32_e32 v16, v16
	v_mul_f32_e32 v13, v13, v41
	v_mul_f32_e32 v17, v17, v41
	v_or3_b32 v27, v18, v22, v21
	v_add_u32_e32 v18, 8, v10
	v_and_b32_e32 v10, 15, v10
	v_cvt_i32_f32_e32 v12, v12
	v_med3_f32 v16, v16, s64, v120
	v_rndne_f32_e32 v13, v13
	v_rndne_f32_e32 v17, v17
	v_cndmask_b32_e64 v10, v10, v18, s[8:9]
	v_add_u32_e32 v18, 8, v14
	v_and_b32_e32 v14, 15, v14
	v_cvt_i32_f32_e32 v16, v16
	v_med3_f32 v13, v13, s64, v120
	v_med3_f32 v17, v17, s64, v120
	v_cndmask_b32_e64 v14, v14, v18, s[8:9]
	v_add_u32_e32 v18, 8, v11
	v_and_b32_e32 v11, 15, v11
	v_cvt_i32_f32_e32 v13, v13
	v_cvt_i32_f32_e32 v17, v17
	v_cndmask_b32_e64 v11, v11, v18, s[8:9]
	v_add_u32_e32 v18, 8, v15
	v_and_b32_e32 v15, 15, v15
	v_mul_f32_e32 v2, v2, v41
	v_cndmask_b32_e64 v15, v15, v18, s[8:9]
	v_add_u32_e32 v18, 8, v12
	v_and_b32_e32 v12, 15, v12
	v_rndne_f32_e32 v2, v2
	v_mul_f32_e32 v6, v6, v41
	v_cndmask_b32_e64 v12, v12, v18, s[8:9]
	v_add_u32_e32 v18, 8, v16
	v_and_b32_e32 v16, 15, v16
	v_med3_f32 v2, v2, s64, v120
	v_rndne_f32_e32 v6, v6
	v_mul_f32_e32 v3, v3, v41
	v_cndmask_b32_e64 v16, v16, v18, s[8:9]
	v_add_u32_e32 v18, 8, v13
	v_lshlrev_b32_e32 v17, 4, v17
	v_cvt_i32_f32_e32 v2, v2
	v_med3_f32 v6, v6, s64, v120
	v_rndne_f32_e32 v3, v3
	v_mul_f32_e32 v7, v7, v41
	v_lshlrev_b32_e32 v16, 20, v16
	v_lshlrev_b32_e32 v12, 16, v12
	v_bitop3_b32 v18, v17, v18, s65 bitop3:0xde
	v_and_or_b32 v13, v13, 15, v17
	v_cvt_i32_f32_e32 v6, v6
	v_med3_f32 v3, v3, s64, v120
	v_rndne_f32_e32 v7, v7
	v_mul_f32_e32 v4, v4, v41
	v_lshlrev_b32_e32 v15, 12, v15
	v_lshlrev_b32_e32 v11, 8, v11
	v_cndmask_b32_e64 v13, v13, v18, s[8:9]
	v_or3_b32 v10, v12, v10, v16
	v_cvt_i32_f32_e32 v3, v3
	v_med3_f32 v7, v7, s64, v120
	v_rndne_f32_e32 v4, v4
	v_mul_f32_e32 v8, v8, v41
	v_mul_f32_e32 v29, v29, v41
	v_mul_f32_e32 v33, v33, v41
	v_lshlrev_b32_e32 v14, 4, v14
	v_lshlrev_b32_e32 v13, 24, v13
	v_or3_b32 v10, v10, v11, v15
	v_cvt_i32_f32_e32 v7, v7
	v_med3_f32 v4, v4, s64, v120
	v_rndne_f32_e32 v8, v8
	v_mul_f32_e32 v30, v30, v41
	v_rndne_f32_e32 v29, v29
	v_rndne_f32_e32 v33, v33
	v_or3_b32 v28, v10, v14, v13
	v_add_u32_e32 v10, 8, v2
	v_and_b32_e32 v2, 15, v2
	v_cvt_i32_f32_e32 v4, v4
	v_med3_f32 v8, v8, s64, v120
	v_mul_f32_e32 v5, v5, v41
	v_mul_f32_e32 v9, v9, v41
	v_rndne_f32_e32 v30, v30
	v_med3_f32 v29, v29, s64, v120
	v_med3_f32 v33, v33, s64, v120
	v_cndmask_b32_e64 v2, v2, v10, s[8:9]
	v_add_u32_e32 v10, 8, v6
	v_and_b32_e32 v6, 15, v6
	v_cvt_i32_f32_e32 v8, v8
	v_rndne_f32_e32 v5, v5
	v_rndne_f32_e32 v9, v9
	v_med3_f32 v30, v30, s64, v120
	v_cvt_i32_f32_e32 v29, v29
	v_cvt_i32_f32_e32 v33, v33
	v_cndmask_b32_e64 v6, v6, v10, s[8:9]
	v_add_u32_e32 v10, 8, v3
	v_and_b32_e32 v3, 15, v3
	v_med3_f32 v5, v5, s64, v120
	v_med3_f32 v9, v9, s64, v120
	v_cvt_i32_f32_e32 v30, v30
	v_cndmask_b32_e64 v3, v3, v10, s[8:9]
	v_add_u32_e32 v10, 8, v7
	v_and_b32_e32 v7, 15, v7
	v_cvt_i32_f32_e32 v5, v5
	v_cvt_i32_f32_e32 v9, v9
	v_cndmask_b32_e64 v7, v7, v10, s[8:9]
	v_add_u32_e32 v10, 8, v4
	v_and_b32_e32 v4, 15, v4
	v_cndmask_b32_e64 v4, v4, v10, s[8:9]
	v_add_u32_e32 v10, 8, v8
	v_and_b32_e32 v8, 15, v8
	v_add_u32_e32 v42, 8, v29
	v_lshlrev_b32_e32 v33, 4, v33
	v_cndmask_b32_e64 v8, v8, v10, s[8:9]
	v_add_u32_e32 v43, 8, v30
	v_and_b32_e32 v30, 15, v30
	v_bitop3_b32 v42, v33, v42, s65 bitop3:0xde
	v_and_or_b32 v29, v29, 15, v33
	v_lshlrev_b32_e32 v8, 20, v8
	v_lshlrev_b32_e32 v4, 16, v4
	v_add_u32_e32 v10, 8, v5
	v_lshlrev_b32_e32 v9, 4, v9
	v_cndmask_b32_e64 v30, v30, v43, s[8:9]
	v_cndmask_b32_e64 v29, v29, v42, s[8:9]
	v_lshlrev_b32_e32 v7, 12, v7
	v_lshlrev_b32_e32 v3, 8, v3
	v_bitop3_b32 v10, v9, v10, s65 bitop3:0xde
	v_and_or_b32 v5, v5, 15, v9
	s_mov_b64 vcc, s[8:9]
	v_or3_b32 v2, v4, v2, v8
	v_lshlrev_b32_e32 v30, 4, v30
	v_lshlrev_b32_e32 v29, 24, v29
	v_lshlrev_b32_e32 v6, 4, v6
	v_cndmask_b32_sdwa v5, v5, v10, vcc dst_sel:BYTE_3 dst_unused:UNUSED_PAD src0_sel:DWORD src1_sel:DWORD
	v_or3_b32 v2, v2, v3, v7
	v_or3_b32 v26, v26, v30, v29
	v_or3_b32 v29, v2, v6, v5
	global_store_dwordx4 v[36:37], v[26:29], off
	s_and_saveexec_b64 s[0:1], s[6:7]
	s_cbranch_execz .LBB0_1111
	global_store_dword v[34:35], v40, off
	s_branch .LBB0_1111
.LBB0_1130:
	s_or_b64 exec, exec, s[22:23]
	v_readlane_b32 s56, v250, 6
	v_readlane_b32 s57, v250, 7
	v_readlane_b32 s58, v250, 8
	v_readlane_b32 s59, v250, 9
